# P3 loop head: K-fragment LDS reads issued before the next-tile global loads (loads fill the LDS latency shadow); uniform-branch chain trimmed
# baseline (speedup 1.0000x reference)
; template <int MODE>
; __device__ void attn_item(const Params& p, char* lds, int grp  , int b, int h, int qblk, int dry) {
;     ...
;   auto gloadK = [&](int kt) {
;     const bf16_t* ktile = kg + (size_t)kt * 64 * LDH;
; #pragma unroll
;     for (int i = 0; i < NKC; ++i) {
;       if (MODE == 0) rk[i] = *(const u32x4*)(ktile + koff[i]);
;       else {
;         const int q = tid + 256 * i; const int row = q / KCH, ch = q % KCH;
;         const bf16_t* src = (ch < 8) ? kg + (size_t)(kt * 64 + row) * LDH + ch * 8 : kpe + (size_t)(kt * 64 + row) * 32 + (ch - 8) * 8;
;         rk[i] = *(const u32x4*)src;
;       }
;     }
;   };
;   auto gloadV = [&](int kt) {
;     const bf16_t* vtile = vg + kt * 64;
; #pragma unroll
;     for (int i = 0; i < NVC; ++i) rv[i] = *(const u32x4*)(vtile + voff[i]);
;   };
;     ...
;   for (int kt = 0; kt < nkt; ++kt) {
;     const bool more = (kt + 1 < nkt);
;     if (more) { gloadK(kt + 1); if (MODE == 1) gloadV(kt + 1); }
;     if (active && kt <= my_last) {
;       const char* base = lds + (kt & 1) * BUF;
;       f32x16 S[2];
;       const char* kp0 = base + l31 * KSTR + comp * 128 + hh * 16;
;       {
;         bf16x8 kf0[DQ / 16], kf1[DQ / 16];
; #pragma unroll
;         for (int ks = 0; ks < DQ / 16; ++ks) kf0[ks] = *(const bf16x8*)(kp0 + ks * 32);
.LBB0_448:
	s_add_i32 s3, s27, 1
	s_cmp_lt_u32 s3, s26
	s_cselect_b64 s[0:1], -1, 0
	s_bitcmp1_b32 s27, 0
	s_cselect_b32 s27, 0x8c00, 0
	v_add_u32_e32 v64, s27, v193
	v_add3_u32 v220, v64, v194, v182
	ds_read_b128 v[64:67], v220
	ds_read_b128 v[68:71], v220 offset:32
	ds_read_b128 v[72:75], v220 offset:64
	ds_read_b128 v[76:79], v220 offset:96
	s_cmp_ge_u32 s3, s26
	s_cbranch_scc1 .LBB0_450
	v_lshl_add_u64 v[216:217], s[50:51], 0, v[152:153]
	v_lshl_add_u64 v[218:219], s[50:51], 0, v[154:155]
	global_load_dwordx4 v[112:115], v[216:217], off
	global_load_dwordx4 v[116:119], v[218:219], off
	v_lshl_add_u64 v[216:217], s[50:51], 0, v[156:157]
	v_lshl_add_u64 v[218:219], s[50:51], 0, v[158:159]
	global_load_dwordx4 v[120:123], v[216:217], off
	global_load_dwordx4 v[124:127], v[218:219], off
	s_lshl_b64 s[44:45], s[24:25], 1
	s_add_u32 s44, s48, s44
	s_addc_u32 s45, s49, s45
	global_load_dwordx4 v[128:131], v212, s[44:45]
	global_load_dwordx4 v[132:135], v213, s[44:45]
	global_load_dwordx4 v[136:139], v214, s[44:45]
	global_load_dwordx4 v[140:143], v215, s[44:45]
; __device__ __forceinline__ f32x16 mfma32(bf16x8 a, bf16x8 b, f32x16 c) { return __builtin_amdgcn_mfma_f32_32x32x16_bf16(a, b, c, 0, 0, 0); }
; __device__ __forceinline__ int accrow(int reg, int hh) { return (reg & 3) + 8 * (reg >> 2) + 4 * hh; }
; template <int MODE>
; __device__ void attn_item(const Params& p, char* lds, int grp  , int b, int h, int qblk, int dry) {
;     ...
;       const char* kp0 = base + l31 * KSTR + comp * 128 + hh * 16;
;       {
;         bf16x8 kf0[DQ / 16], kf1[DQ / 16];
; #pragma unroll
;         for (int ks = 0; ks < DQ / 16; ++ks) kf0[ks] = *(const bf16x8*)(kp0 + ks * 32);
;         __builtin_amdgcn_sched_barrier(0);
; #pragma unroll
;         for (int ks = 0; ks < DQ / 16; ++ks) kf1[ks] = *(const bf16x8*)(kp0 + 32 * KSTR + ks * 32);
; #pragma unroll
;         for (int r = 0; r < 16; ++r) { S[0][r] = 0.f; S[1][r] = 0.f; }
; #pragma unroll
;         for (int ks = 0; ks < DQ / 16; ++ks) S[0] = mfma32(kf0[ks], qf[ks], S[0]);
; #pragma unroll
;         for (int ks = 0; ks < DQ / 16; ++ks) S[1] = mfma32(kf1[ks], qf[ks], S[1]);
;       }
;       if (MODE == 0) {
;         const int kpos0 = kt * 64;
;         if (kpos0 + 63 > qpos0 - 91) {
; #pragma unroll
;           for (int sub = 0; sub < 2; ++sub)
; #pragma unroll
;             for (int r = 0; r < 16; ++r) {
;               int rel = kpos0 + sub * 32 + accrow(r, hh) - qpos; rel = rel < -128 ? -128 : rel;
;               S[sub][r] += s_bt[rel + 128];
;             }
;         }
.LBB0_450:
	s_waitcnt lgkmcnt(3)
	v_mfma_f32_32x32x16_bf16 v[80:95], v[64:67], v[96:99], 0
	ds_read_b128 v[64:67], v220 offset:8704
	ds_read_b128 v[216:219], v220 offset:8736
	ds_read_b128 v[238:241], v220 offset:8768
	ds_read_b128 v[242:245], v220 offset:8800
	s_add_i32 s44, s24, -1
	s_cmp_le_i32 s44, s2
	s_waitcnt lgkmcnt(6)
	v_mfma_f32_32x32x16_bf16 v[80:95], v[68:71], v[100:103], v[80:95]
	s_waitcnt lgkmcnt(5)
	v_mfma_f32_32x32x16_bf16 v[80:95], v[72:75], v[104:107], v[80:95]
	s_waitcnt lgkmcnt(4)
	v_mfma_f32_32x32x16_bf16 v[80:95], v[76:79], v[108:111], v[80:95]
	s_waitcnt lgkmcnt(3)
	v_mfma_f32_32x32x16_bf16 v[64:79], v[64:67], v[96:99], 0
	s_waitcnt lgkmcnt(2)
	v_mfma_f32_32x32x16_bf16 v[64:79], v[216:219], v[100:103], v[64:79]
	s_waitcnt lgkmcnt(1)
	v_mfma_f32_32x32x16_bf16 v[64:79], v[238:241], v[104:107], v[64:79]
	s_waitcnt lgkmcnt(0)
	v_mfma_f32_32x32x16_bf16 v[64:79], v[242:245], v[108:111], v[64:79]
	s_cbranch_scc1 .LBB0_452
	v_add_u32_e32 v220, s24, v165
	v_subrev_u32_e32 v216, 64, v220
	v_max_i32_e32 v216, 0xffffff80, v216
	v_lshl_add_u32 v238, v216, 2, v210
	v_subrev_u32_e32 v216, 63, v220
	v_max_i32_e32 v216, 0xffffff80, v216
	v_lshl_add_u32 v239, v216, 2, v210
	v_subrev_u32_e32 v216, 62, v220
	v_max_i32_e32 v216, 0xffffff80, v216
	v_lshl_add_u32 v240, v216, 2, v210
	v_subrev_u32_e32 v216, 61, v220
	v_max_i32_e32 v216, 0xffffff80, v216
	v_lshl_add_u32 v241, v216, 2, v210
	v_subrev_u32_e32 v216, 56, v220
	v_max_i32_e32 v216, 0xffffff80, v216
	v_lshl_add_u32 v242, v216, 2, v210
	v_subrev_u32_e32 v216, 55, v220
	v_max_i32_e32 v216, 0xffffff80, v216
	v_lshl_add_u32 v243, v216, 2, v210
	v_subrev_u32_e32 v216, 54, v220
	v_max_i32_e32 v216, 0xffffff80, v216
	v_lshl_add_u32 v244, v216, 2, v210
	v_subrev_u32_e32 v216, 53, v220
	v_max_i32_e32 v216, 0xffffff80, v216
	v_lshl_add_u32 v245, v216, 2, v210
	v_subrev_u32_e32 v216, 48, v220
	v_subrev_u32_e32 v217, 47, v220
	v_subrev_u32_e32 v218, 46, v220
	v_subrev_u32_e32 v219, 45, v220
	v_subrev_u32_e32 v234, 40, v220
	v_subrev_u32_e32 v235, 39, v220
	v_subrev_u32_e32 v236, 38, v220
	v_subrev_u32_e32 v237, 37, v220
	v_max_i32_e32 v216, 0xffffff80, v216
	v_max_i32_e32 v217, 0xffffff80, v217
	v_max_i32_e32 v218, 0xffffff80, v218
	v_max_i32_e32 v219, 0xffffff80, v219
	v_max_i32_e32 v234, 0xffffff80, v234
	v_max_i32_e32 v235, 0xffffff80, v235
	v_max_i32_e32 v236, 0xffffff80, v236
	v_max_i32_e32 v237, 0xffffff80, v237
	v_lshl_add_u32 v216, v216, 2, v210
	v_lshl_add_u32 v217, v217, 2, v210
	v_lshl_add_u32 v218, v218, 2, v210
	v_lshl_add_u32 v219, v219, 2, v210
	v_lshl_add_u32 v234, v234, 2, v210
	v_lshl_add_u32 v235, v235, 2, v210
	v_lshl_add_u32 v236, v236, 2, v210
	v_lshl_add_u32 v237, v237, 2, v210
	ds_read_b32 v216, v216
	ds_read_b32 v217, v217
	ds_read_b32 v218, v218
	ds_read_b32 v219, v219
	ds_read_b32 v234, v234
	ds_read_b32 v235, v235
	ds_read_b32 v236, v236
	ds_read_b32 v237, v237
	ds_read_b32 v238, v238
	ds_read_b32 v239, v239
	ds_read_b32 v240, v240
	ds_read_b32 v241, v241
	ds_read_b32 v242, v242
	ds_read_b32 v243, v243
	ds_read_b32 v244, v244
	ds_read_b32 v245, v245
	s_waitcnt lgkmcnt(14)
	v_add_f32_e32 v88, v88, v216
	v_add_f32_e32 v89, v89, v217
	v_subrev_u32_e32 v216, 32, v220
	v_max_i32_e32 v216, 0xffffff80, v216
	s_waitcnt lgkmcnt(6)
	v_add_f32_e32 v80, v80, v238
	v_add_f32_e32 v81, v81, v239
	v_lshl_add_u32 v238, v216, 2, v210
	v_subrev_u32_e32 v216, 31, v220
	v_max_i32_e32 v216, 0xffffff80, v216
	v_lshl_add_u32 v239, v216, 2, v210
	v_subrev_u32_e32 v216, 30, v220
	v_max_i32_e32 v216, 0xffffff80, v216
	s_waitcnt lgkmcnt(4)
	v_add_f32_e32 v82, v82, v240
	v_add_f32_e32 v83, v83, v241
	v_lshl_add_u32 v240, v216, 2, v210
	v_subrev_u32_e32 v216, 29, v220
	v_max_i32_e32 v216, 0xffffff80, v216
	v_lshl_add_u32 v241, v216, 2, v210
	v_subrev_u32_e32 v216, 24, v220
	v_max_i32_e32 v216, 0xffffff80, v216
	s_waitcnt lgkmcnt(2)
	v_add_f32_e32 v84, v84, v242
	v_add_f32_e32 v85, v85, v243
	v_lshl_add_u32 v242, v216, 2, v210
	v_subrev_u32_e32 v216, 23, v220
	v_max_i32_e32 v216, 0xffffff80, v216
	v_lshl_add_u32 v243, v216, 2, v210
	v_subrev_u32_e32 v216, 22, v220
	v_max_i32_e32 v216, 0xffffff80, v216
	s_waitcnt lgkmcnt(0)
	v_add_f32_e32 v86, v86, v244
	v_add_f32_e32 v87, v87, v245
	v_lshl_add_u32 v244, v216, 2, v210
	v_subrev_u32_e32 v216, 21, v220
	v_max_i32_e32 v216, 0xffffff80, v216
	v_add_f32_e32 v94, v94, v236
	v_add_f32_e32 v95, v95, v237
	v_add_f32_e32 v92, v92, v234
	v_add_f32_e32 v93, v93, v235
	v_add_f32_e32 v90, v90, v218
	v_add_f32_e32 v91, v91, v219
	v_lshl_add_u32 v245, v216, 2, v210
	v_add_u32_e32 v216, -16, v220
	v_add_u32_e32 v217, -15, v220
	v_add_u32_e32 v218, -14, v220
	v_add_u32_e32 v219, -13, v220
	v_add_u32_e32 v234, -8, v220
	v_add_u32_e32 v235, -7, v220
	v_add_u32_e32 v236, -6, v220
	v_max_i32_e32 v216, 0xffffff80, v216
	v_max_i32_e32 v217, 0xffffff80, v217
	v_max_i32_e32 v218, 0xffffff80, v218
	v_max_i32_e32 v219, 0xffffff80, v219
	v_max_i32_e32 v234, 0xffffff80, v234
	v_max_i32_e32 v235, 0xffffff80, v235
	v_max_i32_e32 v236, 0xffffff80, v236
	v_add_u32_e32 v220, -5, v220
	v_lshl_add_u32 v216, v216, 2, v210
	v_lshl_add_u32 v217, v217, 2, v210
	v_lshl_add_u32 v218, v218, 2, v210
	v_lshl_add_u32 v219, v219, 2, v210
	v_lshl_add_u32 v234, v234, 2, v210
	v_lshl_add_u32 v235, v235, 2, v210
	v_lshl_add_u32 v236, v236, 2, v210
	v_max_i32_e32 v220, 0xffffff80, v220
	v_lshl_add_u32 v220, v220, 2, v210
	ds_read_b32 v216, v216
	ds_read_b32 v217, v217
	ds_read_b32 v218, v218
	ds_read_b32 v219, v219
	ds_read_b32 v234, v234
	ds_read_b32 v235, v235
	ds_read_b32 v236, v236
	ds_read_b32 v237, v220
	ds_read_b32 v238, v238
	ds_read_b32 v239, v239
	ds_read_b32 v240, v240
	ds_read_b32 v241, v241
	ds_read_b32 v242, v242
	ds_read_b32 v243, v243
	ds_read_b32 v244, v244
	ds_read_b32 v245, v245
	s_waitcnt lgkmcnt(8)
	v_add_f32_e32 v78, v78, v236
	v_add_f32_e32 v79, v79, v237
	v_add_f32_e32 v76, v76, v234
	v_add_f32_e32 v77, v77, v235
	v_add_f32_e32 v74, v74, v218
	v_add_f32_e32 v75, v75, v219
	v_add_f32_e32 v72, v72, v216
	v_add_f32_e32 v73, v73, v217
	s_waitcnt lgkmcnt(0)
	v_add_f32_e32 v70, v70, v244
	v_add_f32_e32 v71, v71, v245
	v_add_f32_e32 v68, v68, v242
	v_add_f32_e32 v69, v69, v243
	v_add_f32_e32 v66, v66, v240
	v_add_f32_e32 v67, v67, v241
	v_add_f32_e32 v64, v64, v238
	v_add_f32_e32 v65, v65, v239
